# in-proj K-loop shifted by one s_nop back to the baseline's byte phase (mod 8) on top of v81
# baseline (speedup 1.0000x reference)
; #define PG8_STAGE(bufoff, gbase, voff) do { _Pragma("unroll") for (int _i = 0; _i < 2; ++_i) \
;         __builtin_amdgcn_global_load_lds((const unsigned*)((const char*)(gbase) + (voff)[_i]), (LAS unsigned*)(lds + (bufoff) + ldsw + _i * 8192), 16, 0, 0); } while (0)
; #define PG8_LDA(dst, b, h) do { _Pragma("unroll") for (int m = 0; m < 4; ++m) _Pragma("unroll") for (int k = 0; k < 2; ++k) dst[m][k] = *(const LAS bf16x8*)(lds + PG8_SA(b, h) + aoff + m * 2048 + k * 1024); } while (0)
; #define PG8_LDB(dst, b, h) do { _Pragma("unroll") for (int n = 0; n < 2; ++n) _Pragma("unroll") for (int k = 0; k < 2; ++k) dst[n][k] = *(const LAS bf16x8*)(lds + PG8_SB(b, h) + boff + n * 2048 + k * 1024); } while (0)
; #define PG8_MMA(ai, bj, At, Bt) do { __builtin_amdgcn_s_setprio(1); _Pragma("unroll") for (int m = 0; m < 4; ++m) _Pragma("unroll") for (int n = 0; n < 2; ++n) _Pragma("unroll") for (int k = 0; k < 2; ++k) \
;         acc[ai][bj][m][n] = __builtin_amdgcn_mfma_f32_16x16x32_bf16(Bt[n][k], At[m][k], acc[ai][bj][m][n], 0, 0, 0); __builtin_amdgcn_s_setprio(0); } while (0)
; #define PG8_WAIT_V(n) asm volatile("s_waitcnt vmcnt(" #n ")" ::: "memory")
; #define PG8_WAIT_L(n) asm volatile("s_waitcnt lgkmcnt(" #n ")" ::: "memory")
; #define PG8_BAR __builtin_amdgcn_s_barrier()
; #define PG8_SCHED __builtin_amdgcn_sched_barrier(0)
; template <class Epi>
; DI void gemm_phase(LAS unsigned char* lds, const Gemm g, const Order& S, const Epi& E, const int wv) {
;     ...
;         const bool has_next = S.next(ui + 1, nxt);
;         const char* nA = has_next ? (const char*)g.A + (size_t)nxt.pm * tstep + (size_t)nxt.kofs * 2 : cA; const char* nB = has_next ? (const char*)g.Bt + (size_t)nxt.pn * tstep + (size_t)nxt.kofs * 2 : cB;
;         const int nt = cur.nt;
;         for (int t = 0; t < nt; t += 2) {
;             const bool last = (t == nt - 2);
;             const char* a1 = cA + (size_t)(t + 1) * kstep;
;             const char* a2 = last ? nA : cA + (size_t)(t + 2) * kstep; const char* b2 = last ? nB : cB + (size_t)(t + 2) * kstep;
;             const char* a3 = a2 + kstep; const char* b3 = b2 + kstep;
;             PG8_LDB(B0, 0, 0); PG8_LDB(B1, 0, 1); PG8_SCHED; PG8_LDA(At, 0, 0); PG8_STAGE(PG8_SA(1, 1), a1 + hstep, voffA);
;             PG8_WAIT_V(8); PG8_WAIT_L(0); PG8_BAR; PG8_MMA(0, 0, At, B0); PG8_MMA(0, 1, At, B1); PG8_BAR; PG8_SCHED;
.LBB0_154:
	s_ashr_i32 s7, s6, 31
	s_lshl_b64 s[8:9], s[6:7], 19
	v_readlane_b32 s10, v254, 14
	v_readlane_b32 s11, v254, 15
	s_add_u32 s8, s10, s8
	s_addc_u32 s9, s11, s9
	s_and_b64 s[10:11], s[0:1], exec
	s_cselect_b32 s7, s9, s5
	s_cselect_b32 s27, s8, s4
	s_ashr_i32 s3, s2, 31
	s_lshl_b64 s[10:11], s[2:3], 19
	s_add_u32 s10, s16, s10
	s_addc_u32 s11, s17, s11
	s_and_b64 s[14:15], s[0:1], exec
	s_cselect_b32 s3, s11, s13
	s_cselect_b32 s28, s10, s12
	s_add_u32 s4, s4, 0x40080
	s_addc_u32 s5, s5, 0
	s_add_u32 s29, s12, 0x100
	v_mov_b32_e32 v0, 0
	s_addc_u32 s30, s13, 0
	s_mov_b32 s31, -2
	v_mov_b32_e32 v1, v0
	v_mov_b32_e32 v2, v0
	v_mov_b32_e32 v3, v0
	v_mov_b32_e32 v4, v0
	v_mov_b32_e32 v5, v0
	v_mov_b32_e32 v6, v0
	v_mov_b32_e32 v7, v0
	v_mov_b32_e32 v16, v0
	v_mov_b32_e32 v17, v0
	v_mov_b32_e32 v18, v0
	v_mov_b32_e32 v19, v0
	v_mov_b32_e32 v20, v0
	v_mov_b32_e32 v21, v0
	v_mov_b32_e32 v22, v0
	v_mov_b32_e32 v23, v0
	v_mov_b32_e32 v32, v0
	v_mov_b32_e32 v33, v0
	v_mov_b32_e32 v34, v0
	v_mov_b32_e32 v35, v0
	v_mov_b32_e32 v36, v0
	v_mov_b32_e32 v37, v0
	v_mov_b32_e32 v38, v0
	v_mov_b32_e32 v39, v0
	v_mov_b32_e32 v48, v0
	v_mov_b32_e32 v49, v0
	v_mov_b32_e32 v50, v0
	v_mov_b32_e32 v51, v0
	v_mov_b32_e32 v52, v0
	v_mov_b32_e32 v53, v0
	v_mov_b32_e32 v54, v0
	v_mov_b32_e32 v55, v0
	v_mov_b32_e32 v8, v0
	v_mov_b32_e32 v9, v0
	v_mov_b32_e32 v10, v0
	v_mov_b32_e32 v11, v0
	v_mov_b32_e32 v12, v0
	v_mov_b32_e32 v13, v0
	v_mov_b32_e32 v14, v0
	v_mov_b32_e32 v15, v0
	v_mov_b32_e32 v24, v0
	v_mov_b32_e32 v25, v0
	v_mov_b32_e32 v26, v0
	v_mov_b32_e32 v27, v0
	v_mov_b32_e32 v28, v0
	v_mov_b32_e32 v29, v0
	v_mov_b32_e32 v30, v0
	v_mov_b32_e32 v31, v0
	v_mov_b32_e32 v40, v0
	v_mov_b32_e32 v41, v0
	v_mov_b32_e32 v42, v0
	v_mov_b32_e32 v43, v0
	v_mov_b32_e32 v44, v0
	v_mov_b32_e32 v45, v0
	v_mov_b32_e32 v46, v0
	v_mov_b32_e32 v47, v0
	v_mov_b32_e32 v56, v0
	v_mov_b32_e32 v57, v0
	v_mov_b32_e32 v58, v0
	v_mov_b32_e32 v59, v0
	v_mov_b32_e32 v60, v0
	v_mov_b32_e32 v61, v0
	v_mov_b32_e32 v62, v0
	v_mov_b32_e32 v63, v0
	v_mov_b32_e32 v64, v0
	v_mov_b32_e32 v65, v0
	v_mov_b32_e32 v66, v0
	v_mov_b32_e32 v67, v0
	v_mov_b32_e32 v68, v0
	v_mov_b32_e32 v69, v0
	v_mov_b32_e32 v70, v0
	v_mov_b32_e32 v71, v0
	v_mov_b32_e32 v80, v0
	v_mov_b32_e32 v81, v0
	v_mov_b32_e32 v82, v0
	v_mov_b32_e32 v83, v0
	v_mov_b32_e32 v84, v0
	v_mov_b32_e32 v85, v0
	v_mov_b32_e32 v86, v0
	v_mov_b32_e32 v87, v0
	v_mov_b32_e32 v96, v0
	v_mov_b32_e32 v97, v0
	v_mov_b32_e32 v98, v0
	v_mov_b32_e32 v99, v0
	v_mov_b32_e32 v100, v0
	v_mov_b32_e32 v101, v0
	v_mov_b32_e32 v102, v0
	v_mov_b32_e32 v103, v0
	v_mov_b32_e32 v114, v0
	v_mov_b32_e32 v115, v0
	v_mov_b32_e32 v116, v0
	v_mov_b32_e32 v117, v0
	v_mov_b32_e32 v118, v0
	v_mov_b32_e32 v119, v0
	v_mov_b32_e32 v120, v0
	v_mov_b32_e32 v121, v0
	v_mov_b32_e32 v72, v0
	v_mov_b32_e32 v73, v0
	v_mov_b32_e32 v74, v0
	v_mov_b32_e32 v75, v0
	v_mov_b32_e32 v76, v0
	v_mov_b32_e32 v77, v0
	v_mov_b32_e32 v78, v0
	v_mov_b32_e32 v79, v0
	v_mov_b32_e32 v88, v0
	v_mov_b32_e32 v89, v0
	v_mov_b32_e32 v90, v0
	v_mov_b32_e32 v91, v0
	v_mov_b32_e32 v92, v0
	v_mov_b32_e32 v93, v0
	v_mov_b32_e32 v94, v0
	v_mov_b32_e32 v95, v0
	v_mov_b32_e32 v104, v0
	v_mov_b32_e32 v105, v0
	v_mov_b32_e32 v106, v0
	v_mov_b32_e32 v107, v0
	v_mov_b32_e32 v108, v0
	v_mov_b32_e32 v109, v0
	v_mov_b32_e32 v110, v0
	v_mov_b32_e32 v111, v0
	v_mov_b32_e32 v122, v0
	v_mov_b32_e32 v123, v0
	v_mov_b32_e32 v124, v0
	v_mov_b32_e32 v125, v0
	v_mov_b32_e32 v126, v0
	v_mov_b32_e32 v127, v0
	v_mov_b32_e32 v128, v0
	v_mov_b32_e32 v129, v0
	v_readlane_b32 s37, v253, 14
	s_mov_b64 s[38:39], 0x80
	s_nop 0
.LBB0_155:
	s_add_u32 s12, s4, 0xfffc0080
	s_addc_u32 s13, s5, -1
	s_add_i32 s33, 0, 0x10000
	s_cmp_eq_u32 s31, 12
	s_cselect_b32 s15, s7, s13
	s_cselect_b32 s14, s27, s12
	v_add_u32_e32 v112, s33, v150
	s_cselect_b32 s13, s3, s30
	s_cselect_b32 s12, s28, s29
	s_add_i32 s36, 0, 0x14000
	ds_read_b128 v[142:145], v112
	ds_read_b128 v[156:159], v112 offset:1024
	ds_read_b128 v[160:163], v112 offset:2048
	ds_read_b128 v[164:167], v112 offset:3072
	v_add_u32_e32 v112, s36, v150
	ds_read_b128 v[168:171], v112
	ds_read_b128 v[172:175], v112 offset:1024
	ds_read_b128 v[176:179], v112 offset:2048
	ds_read_b128 v[180:183], v112 offset:3072
	v_lshl_add_u64 v[152:153], s[4:5], 0, v[138:139]
	s_add_i32 m0, s18, 0xc000
	ds_read_b128 v[184:187], v154
	ds_read_b128 v[204:207], v154 offset:1024
	ds_read_b128 v[208:211], v154 offset:2048
	ds_read_b128 v[212:215], v154 offset:3072
	ds_read_b128 v[216:219], v154 offset:4096
	ds_read_b128 v[220:223], v154 offset:5120
	ds_read_b128 v[224:227], v154 offset:6144
	ds_read_b128 v[228:231], v154 offset:7168
	global_load_lds_dwordx4 v[152:153], off
	v_lshl_add_u64 v[152:153], s[4:5], 0, v[140:141]
	s_add_i32 m0, s18, 0xe000
	s_nop 0
	global_load_lds_dwordx4 v[152:153], off
	s_waitcnt vmcnt(8)
	s_waitcnt lgkmcnt(0)
	s_barrier
; #define PG8_STAGE(bufoff, gbase, voff) do { _Pragma("unroll") for (int _i = 0; _i < 2; ++_i) \
;         __builtin_amdgcn_global_load_lds((const unsigned*)((const char*)(gbase) + (voff)[_i]), (LAS unsigned*)(lds + (bufoff) + ldsw + _i * 8192), 16, 0, 0); } while (0)
; #define PG8_LDA(dst, b, h) do { _Pragma("unroll") for (int m = 0; m < 4; ++m) _Pragma("unroll") for (int k = 0; k < 2; ++k) dst[m][k] = *(const LAS bf16x8*)(lds + PG8_SA(b, h) + aoff + m * 2048 + k * 1024); } while (0)
; #define PG8_MMA(ai, bj, At, Bt) do { __builtin_amdgcn_s_setprio(1); _Pragma("unroll") for (int m = 0; m < 4; ++m) _Pragma("unroll") for (int n = 0; n < 2; ++n) _Pragma("unroll") for (int k = 0; k < 2; ++k) \
;         acc[ai][bj][m][n] = __builtin_amdgcn_mfma_f32_16x16x32_bf16(Bt[n][k], At[m][k], acc[ai][bj][m][n], 0, 0, 0); __builtin_amdgcn_s_setprio(0); } while (0)
; #define PG8_WAIT_V(n) asm volatile("s_waitcnt vmcnt(" #n ")" ::: "memory")
; #define PG8_WAIT_L(n) asm volatile("s_waitcnt lgkmcnt(" #n ")" ::: "memory")
; #define PG8_BAR __builtin_amdgcn_s_barrier()
; #define PG8_SCHED __builtin_amdgcn_sched_barrier(0)
; template <class Epi>
; DI void gemm_phase(LAS unsigned char* lds, const Gemm g, const Order& S, const Epi& E, const int wv) {
;     ...
;             PG8_WAIT_V(8); PG8_WAIT_L(0); PG8_BAR; PG8_MMA(0, 0, At, B0); PG8_MMA(0, 1, At, B1); PG8_BAR; PG8_SCHED;
;             PG8_LDA(At, 0, 1); PG8_STAGE(PG8_SB(0, 0), b2, voffB); PG8_STAGE(PG8_SB(0, 1), b2 + hstep, voffB); PG8_STAGE(PG8_SA(0, 0), a2, voffA);
;             PG8_WAIT_V(8); PG8_WAIT_L(0); PG8_BAR; PG8_MMA(1, 0, At, B0); PG8_MMA(1, 1, At, B1); PG8_BAR; PG8_SCHED;
	s_setprio 1
	s_waitcnt lgkmcnt(0)
	v_mfma_f32_16x16x32_bf16 v[126:129], v[142:145], v[184:187], v[126:129]
	v_mfma_f32_16x16x32_bf16 v[122:125], v[160:163], v[184:187], v[122:125]
	v_mfma_f32_16x16x32_bf16 v[108:111], v[142:145], v[208:211], v[108:111]
	v_mfma_f32_16x16x32_bf16 v[104:107], v[160:163], v[208:211], v[104:107]
	v_mfma_f32_16x16x32_bf16 v[92:95], v[142:145], v[216:219], v[92:95]
	v_mfma_f32_16x16x32_bf16 v[88:91], v[160:163], v[216:219], v[88:91]
	v_mfma_f32_16x16x32_bf16 v[76:79], v[142:145], v[224:227], v[76:79]
	v_mfma_f32_16x16x32_bf16 v[72:75], v[160:163], v[224:227], v[72:75]
	v_mfma_f32_16x16x32_bf16 v[126:129], v[156:159], v[204:207], v[126:129]
	v_mfma_f32_16x16x32_bf16 v[122:125], v[164:167], v[204:207], v[122:125]
	v_mfma_f32_16x16x32_bf16 v[108:111], v[156:159], v[212:215], v[108:111]
	v_mfma_f32_16x16x32_bf16 v[104:107], v[164:167], v[212:215], v[104:107]
	v_mfma_f32_16x16x32_bf16 v[92:95], v[156:159], v[220:223], v[92:95]
	v_mfma_f32_16x16x32_bf16 v[88:91], v[164:167], v[220:223], v[88:91]
	v_mfma_f32_16x16x32_bf16 v[76:79], v[156:159], v[228:231], v[76:79]
	v_mfma_f32_16x16x32_bf16 v[72:75], v[164:167], v[228:231], v[72:75]
	s_setprio 0
	s_setprio 1
	v_mfma_f32_16x16x32_bf16 v[118:121], v[168:171], v[184:187], v[118:121]
	v_mfma_f32_16x16x32_bf16 v[114:117], v[176:179], v[184:187], v[114:117]
	v_mfma_f32_16x16x32_bf16 v[100:103], v[168:171], v[208:211], v[100:103]
	v_mfma_f32_16x16x32_bf16 v[96:99], v[176:179], v[208:211], v[96:99]
	v_mfma_f32_16x16x32_bf16 v[84:87], v[168:171], v[216:219], v[84:87]
	v_mfma_f32_16x16x32_bf16 v[80:83], v[176:179], v[216:219], v[80:83]
	v_mfma_f32_16x16x32_bf16 v[68:71], v[168:171], v[224:227], v[68:71]
	v_mfma_f32_16x16x32_bf16 v[64:67], v[176:179], v[224:227], v[64:67]
	v_mfma_f32_16x16x32_bf16 v[118:121], v[172:175], v[204:207], v[118:121]
	v_mfma_f32_16x16x32_bf16 v[114:117], v[180:183], v[204:207], v[114:117]
	v_mfma_f32_16x16x32_bf16 v[100:103], v[172:175], v[212:215], v[100:103]
	v_mfma_f32_16x16x32_bf16 v[96:99], v[180:183], v[212:215], v[96:99]
	v_mfma_f32_16x16x32_bf16 v[84:87], v[172:175], v[220:223], v[84:87]
	v_mfma_f32_16x16x32_bf16 v[80:83], v[180:183], v[220:223], v[80:83]
	v_mfma_f32_16x16x32_bf16 v[68:71], v[172:175], v[228:231], v[68:71]
	v_mfma_f32_16x16x32_bf16 v[64:67], v[180:183], v[228:231], v[64:67]
	s_setprio 0
	s_barrier
	s_add_i32 s33, s33, s37
	v_lshl_add_u64 v[152:153], s[12:13], 0, v[134:135]
	s_mov_b32 m0, s33
	ds_read_b128 v[184:187], v154 offset:16384
	ds_read_b128 v[204:207], v154 offset:17408
	ds_read_b128 v[208:211], v154 offset:18432
	ds_read_b128 v[212:215], v154 offset:19456
	ds_read_b128 v[216:219], v154 offset:20480
	ds_read_b128 v[220:223], v154 offset:21504
	ds_read_b128 v[224:227], v154 offset:22528
	ds_read_b128 v[228:231], v154 offset:23552
	global_load_lds_dwordx4 v[152:153], off
	s_add_i32 m0, s33, 0x2000
	s_add_u32 s34, s12, 0x40000
	v_lshl_add_u64 v[188:189], s[12:13], 0, v[130:131]
	s_addc_u32 s35, s13, 0
	s_add_i32 s33, s36, s37
	global_load_lds_dwordx4 v[188:189], off
	v_lshl_add_u64 v[192:193], s[34:35], 0, v[134:135]
	s_mov_b32 m0, s33
	v_lshl_add_u64 v[194:195], s[14:15], 0, v[132:133]
	global_load_lds_dwordx4 v[192:193], off
	v_lshl_add_u64 v[192:193], s[34:35], 0, v[130:131]
	s_add_i32 m0, s33, 0x2000
	s_nop 0
	global_load_lds_dwordx4 v[192:193], off
	v_lshl_add_u64 v[192:193], s[14:15], 0, v[136:137]
	s_mov_b32 m0, s18
	s_nop 0
	global_load_lds_dwordx4 v[192:193], off
	s_mov_b32 m0, s19
	s_nop 0
	global_load_lds_dwordx4 v[194:195], off
	s_waitcnt vmcnt(8)
	s_waitcnt lgkmcnt(0)
	s_barrier
	s_setprio 1
	s_waitcnt lgkmcnt(0)
	v_mfma_f32_16x16x32_bf16 v[60:63], v[142:145], v[184:187], v[60:63]
	v_mfma_f32_16x16x32_bf16 v[56:59], v[160:163], v[184:187], v[56:59]
	v_mfma_f32_16x16x32_bf16 v[44:47], v[142:145], v[208:211], v[44:47]
	v_mfma_f32_16x16x32_bf16 v[40:43], v[160:163], v[208:211], v[40:43]
	v_mfma_f32_16x16x32_bf16 v[28:31], v[142:145], v[216:219], v[28:31]
	v_mfma_f32_16x16x32_bf16 v[24:27], v[160:163], v[216:219], v[24:27]
	v_mfma_f32_16x16x32_bf16 v[12:15], v[142:145], v[224:227], v[12:15]
	v_mfma_f32_16x16x32_bf16 v[8:11], v[160:163], v[224:227], v[8:11]
	v_mfma_f32_16x16x32_bf16 v[60:63], v[156:159], v[204:207], v[60:63]
	v_mfma_f32_16x16x32_bf16 v[56:59], v[164:167], v[204:207], v[56:59]
	v_mfma_f32_16x16x32_bf16 v[44:47], v[156:159], v[212:215], v[44:47]
	v_mfma_f32_16x16x32_bf16 v[40:43], v[164:167], v[212:215], v[40:43]
	v_mfma_f32_16x16x32_bf16 v[28:31], v[156:159], v[220:223], v[28:31]
	v_mfma_f32_16x16x32_bf16 v[24:27], v[164:167], v[220:223], v[24:27]
	v_mfma_f32_16x16x32_bf16 v[12:15], v[156:159], v[228:231], v[12:15]
	v_mfma_f32_16x16x32_bf16 v[8:11], v[164:167], v[228:231], v[8:11]
	s_setprio 0
	s_setprio 1
	v_mfma_f32_16x16x32_bf16 v[52:55], v[168:171], v[184:187], v[52:55]
	v_mfma_f32_16x16x32_bf16 v[48:51], v[176:179], v[184:187], v[48:51]
	v_mfma_f32_16x16x32_bf16 v[36:39], v[168:171], v[208:211], v[36:39]
	v_mfma_f32_16x16x32_bf16 v[32:35], v[176:179], v[208:211], v[32:35]
	v_mfma_f32_16x16x32_bf16 v[20:23], v[168:171], v[216:219], v[20:23]
	v_mfma_f32_16x16x32_bf16 v[16:19], v[176:179], v[216:219], v[16:19]
	v_mfma_f32_16x16x32_bf16 v[4:7], v[168:171], v[224:227], v[4:7]
	v_mfma_f32_16x16x32_bf16 v[0:3], v[176:179], v[224:227], v[0:3]
	v_mfma_f32_16x16x32_bf16 v[52:55], v[172:175], v[204:207], v[52:55]
	v_mfma_f32_16x16x32_bf16 v[48:51], v[180:183], v[204:207], v[48:51]
	v_mfma_f32_16x16x32_bf16 v[36:39], v[172:175], v[212:215], v[36:39]
	v_mfma_f32_16x16x32_bf16 v[32:35], v[180:183], v[212:215], v[32:35]
	v_mfma_f32_16x16x32_bf16 v[20:23], v[172:175], v[220:223], v[20:23]
	v_mfma_f32_16x16x32_bf16 v[16:19], v[180:183], v[220:223], v[16:19]
	v_mfma_f32_16x16x32_bf16 v[4:7], v[172:175], v[228:231], v[4:7]
	v_mfma_f32_16x16x32_bf16 v[0:3], v[180:183], v[228:231], v[0:3]
	s_setprio 0
	s_barrier
; #define PG8_STAGE(bufoff, gbase, voff) do { _Pragma("unroll") for (int _i = 0; _i < 2; ++_i) \
;         __builtin_amdgcn_global_load_lds((const unsigned*)((const char*)(gbase) + (voff)[_i]), (LAS unsigned*)(lds + (bufoff) + ldsw + _i * 8192), 16, 0, 0); } while (0)
; #define PG8_LDA(dst, b, h) do { _Pragma("unroll") for (int m = 0; m < 4; ++m) _Pragma("unroll") for (int k = 0; k < 2; ++k) dst[m][k] = *(const LAS bf16x8*)(lds + PG8_SA(b, h) + aoff + m * 2048 + k * 1024); } while (0)
; #define PG8_LDB(dst, b, h) do { _Pragma("unroll") for (int n = 0; n < 2; ++n) _Pragma("unroll") for (int k = 0; k < 2; ++k) dst[n][k] = *(const LAS bf16x8*)(lds + PG8_SB(b, h) + boff + n * 2048 + k * 1024); } while (0)
; #define PG8_MMA(ai, bj, At, Bt) do { __builtin_amdgcn_s_setprio(1); _Pragma("unroll") for (int m = 0; m < 4; ++m) _Pragma("unroll") for (int n = 0; n < 2; ++n) _Pragma("unroll") for (int k = 0; k < 2; ++k) \
;         acc[ai][bj][m][n] = __builtin_amdgcn_mfma_f32_16x16x32_bf16(Bt[n][k], At[m][k], acc[ai][bj][m][n], 0, 0, 0); __builtin_amdgcn_s_setprio(0); } while (0)
; #define PG8_WAIT_V(n) asm volatile("s_waitcnt vmcnt(" #n ")" ::: "memory")
; #define PG8_WAIT_L(n) asm volatile("s_waitcnt lgkmcnt(" #n ")" ::: "memory")
; #define PG8_BAR __builtin_amdgcn_s_barrier()
; #define PG8_SCHED __builtin_amdgcn_sched_barrier(0)
; template <class Epi>
; DI void gemm_phase(LAS unsigned char* lds, const Gemm g, const Order& S, const Epi& E, const int wv) {
;     ...
;             PG8_LDB(B0, 1, 0); PG8_LDB(B1, 1, 1); PG8_SCHED; PG8_LDA(At, 1, 0); PG8_STAGE(PG8_SA(0, 1), a2 + hstep, voffA);
;             PG8_WAIT_V(8); PG8_WAIT_L(0); PG8_BAR; PG8_MMA(0, 0, At, B0); PG8_MMA(0, 1, At, B1); PG8_BAR; PG8_SCHED;
	s_add_i32 s33, 0, 0x18000
	v_add_u32_e32 v112, s33, v150
	s_add_i32 s34, 0, 0x1c000
	ds_read_b128 v[142:145], v112
	ds_read_b128 v[156:159], v112 offset:1024
	ds_read_b128 v[160:163], v112 offset:2048
	ds_read_b128 v[164:167], v112 offset:3072
	v_add_u32_e32 v112, s34, v150
	ds_read_b128 v[168:171], v112
	ds_read_b128 v[172:175], v112 offset:1024
	ds_read_b128 v[176:179], v112 offset:2048
	ds_read_b128 v[180:183], v112 offset:3072
	s_add_u32 s14, s14, 0x40000
	s_addc_u32 s15, s15, 0
	s_mov_b32 m0, s20
	v_lshl_add_u64 v[196:197], s[14:15], 0, v[136:137]
	ds_read_b128 v[184:187], v154 offset:32768
	ds_read_b128 v[204:207], v154 offset:33792
	ds_read_b128 v[208:211], v154 offset:34816
	ds_read_b128 v[212:215], v154 offset:35840
	ds_read_b128 v[216:219], v154 offset:36864
	ds_read_b128 v[220:223], v154 offset:37888
	ds_read_b128 v[224:227], v154 offset:38912
	ds_read_b128 v[228:231], v154 offset:39936
	global_load_lds_dwordx4 v[196:197], off
	v_lshl_add_u64 v[196:197], s[14:15], 0, v[132:133]
	s_mov_b32 m0, s21
	s_nop 0
	global_load_lds_dwordx4 v[196:197], off
	s_waitcnt vmcnt(8)
	s_waitcnt lgkmcnt(0)
	s_barrier
	s_setprio 1
	s_waitcnt lgkmcnt(0)
	v_mfma_f32_16x16x32_bf16 v[126:129], v[142:145], v[184:187], v[126:129]
	v_mfma_f32_16x16x32_bf16 v[122:125], v[160:163], v[184:187], v[122:125]
	v_mfma_f32_16x16x32_bf16 v[108:111], v[142:145], v[208:211], v[108:111]
	v_mfma_f32_16x16x32_bf16 v[104:107], v[160:163], v[208:211], v[104:107]
	v_mfma_f32_16x16x32_bf16 v[92:95], v[142:145], v[216:219], v[92:95]
	v_mfma_f32_16x16x32_bf16 v[88:91], v[160:163], v[216:219], v[88:91]
	v_mfma_f32_16x16x32_bf16 v[76:79], v[142:145], v[224:227], v[76:79]
	v_mfma_f32_16x16x32_bf16 v[72:75], v[160:163], v[224:227], v[72:75]
	v_mfma_f32_16x16x32_bf16 v[126:129], v[156:159], v[204:207], v[126:129]
	v_mfma_f32_16x16x32_bf16 v[122:125], v[164:167], v[204:207], v[122:125]
	v_mfma_f32_16x16x32_bf16 v[108:111], v[156:159], v[212:215], v[108:111]
	v_mfma_f32_16x16x32_bf16 v[104:107], v[164:167], v[212:215], v[104:107]
	v_mfma_f32_16x16x32_bf16 v[92:95], v[156:159], v[220:223], v[92:95]
	v_mfma_f32_16x16x32_bf16 v[88:91], v[164:167], v[220:223], v[88:91]
	v_mfma_f32_16x16x32_bf16 v[76:79], v[156:159], v[228:231], v[76:79]
	v_mfma_f32_16x16x32_bf16 v[72:75], v[164:167], v[228:231], v[72:75]
	s_setprio 0
	s_setprio 1
	v_mfma_f32_16x16x32_bf16 v[118:121], v[168:171], v[184:187], v[118:121]
	v_mfma_f32_16x16x32_bf16 v[114:117], v[176:179], v[184:187], v[114:117]
	v_mfma_f32_16x16x32_bf16 v[100:103], v[168:171], v[208:211], v[100:103]
	v_mfma_f32_16x16x32_bf16 v[96:99], v[176:179], v[208:211], v[96:99]
	v_mfma_f32_16x16x32_bf16 v[84:87], v[168:171], v[216:219], v[84:87]
	v_mfma_f32_16x16x32_bf16 v[80:83], v[176:179], v[216:219], v[80:83]
	v_mfma_f32_16x16x32_bf16 v[68:71], v[168:171], v[224:227], v[68:71]
	v_mfma_f32_16x16x32_bf16 v[64:67], v[176:179], v[224:227], v[64:67]
	v_mfma_f32_16x16x32_bf16 v[118:121], v[172:175], v[204:207], v[118:121]
	v_mfma_f32_16x16x32_bf16 v[114:117], v[180:183], v[204:207], v[114:117]
	v_mfma_f32_16x16x32_bf16 v[100:103], v[172:175], v[212:215], v[100:103]
	v_mfma_f32_16x16x32_bf16 v[96:99], v[180:183], v[212:215], v[96:99]
	v_mfma_f32_16x16x32_bf16 v[84:87], v[172:175], v[220:223], v[84:87]
	v_mfma_f32_16x16x32_bf16 v[80:83], v[180:183], v[220:223], v[80:83]
	v_mfma_f32_16x16x32_bf16 v[68:71], v[172:175], v[228:231], v[68:71]
	v_mfma_f32_16x16x32_bf16 v[64:67], v[180:183], v[228:231], v[64:67]
	s_setprio 0
	s_barrier
; #define PG8_STAGE(bufoff, gbase, voff) do { _Pragma("unroll") for (int _i = 0; _i < 2; ++_i) \
;         __builtin_amdgcn_global_load_lds((const unsigned*)((const char*)(gbase) + (voff)[_i]), (LAS unsigned*)(lds + (bufoff) + ldsw + _i * 8192), 16, 0, 0); } while (0)
; #define PG8_LDA(dst, b, h) do { _Pragma("unroll") for (int m = 0; m < 4; ++m) _Pragma("unroll") for (int k = 0; k < 2; ++k) dst[m][k] = *(const LAS bf16x8*)(lds + PG8_SA(b, h) + aoff + m * 2048 + k * 1024); } while (0)
; #define PG8_MMA(ai, bj, At, Bt) do { __builtin_amdgcn_s_setprio(1); _Pragma("unroll") for (int m = 0; m < 4; ++m) _Pragma("unroll") for (int n = 0; n < 2; ++n) _Pragma("unroll") for (int k = 0; k < 2; ++k) \
;         acc[ai][bj][m][n] = __builtin_amdgcn_mfma_f32_16x16x32_bf16(Bt[n][k], At[m][k], acc[ai][bj][m][n], 0, 0, 0); __builtin_amdgcn_s_setprio(0); } while (0)
; #define PG8_WAIT_V(n) asm volatile("s_waitcnt vmcnt(" #n ")" ::: "memory")
; #define PG8_WAIT_L(n) asm volatile("s_waitcnt lgkmcnt(" #n ")" ::: "memory")
; #define PG8_BAR __builtin_amdgcn_s_barrier()
; #define PG8_SCHED __builtin_amdgcn_sched_barrier(0)
; template <class Epi>
; DI void gemm_phase(LAS unsigned char* lds, const Gemm g, const Order& S, const Epi& E, const int wv) {
;     ...
;             PG8_LDA(At, 1, 1); PG8_STAGE(PG8_SB(1, 0), b3, voffB); PG8_STAGE(PG8_SB(1, 1), b3 + hstep, voffB); PG8_STAGE(PG8_SA(1, 0), a3, voffA);
;             PG8_WAIT_V(8); PG8_WAIT_L(0); PG8_BAR; PG8_MMA(1, 0, At, B0); PG8_MMA(1, 1, At, B1); PG8_BAR; PG8_SCHED;
;         }
;         if (wr == 0) PG8_BAR;
	s_add_i32 s14, s33, s37
	v_lshl_add_u64 v[152:153], v[152:153], 0, s[38:39]
	s_mov_b32 m0, s14
	ds_read_b128 v[184:187], v154 offset:49152
	ds_read_b128 v[204:207], v154 offset:50176
	ds_read_b128 v[208:211], v154 offset:51200
	ds_read_b128 v[212:215], v154 offset:52224
	ds_read_b128 v[216:219], v154 offset:53248
	ds_read_b128 v[220:223], v154 offset:54272
	ds_read_b128 v[224:227], v154 offset:55296
	ds_read_b128 v[228:231], v154 offset:56320
	global_load_lds_dwordx4 v[152:153], off
	s_add_i32 m0, s14, 0x2000
	s_add_u32 s12, s12, 0x40080
	v_lshl_add_u64 v[152:153], v[188:189], 0, s[38:39]
	s_addc_u32 s13, s13, 0
	s_add_i32 s14, s34, s37
	global_load_lds_dwordx4 v[152:153], off
	v_lshl_add_u64 v[152:153], s[12:13], 0, v[134:135]
	s_mov_b32 m0, s14
	s_nop 0
	global_load_lds_dwordx4 v[152:153], off
	v_lshl_add_u64 v[152:153], s[12:13], 0, v[130:131]
	s_add_i32 m0, s14, 0x2000
	s_nop 0
	global_load_lds_dwordx4 v[152:153], off
	v_lshl_add_u64 v[152:153], v[192:193], 0, s[38:39]
	s_mov_b32 m0, s22
	s_nop 0
	global_load_lds_dwordx4 v[152:153], off
	v_lshl_add_u64 v[152:153], v[194:195], 0, s[38:39]
	s_mov_b32 m0, s23
	s_nop 0
	global_load_lds_dwordx4 v[152:153], off
	s_waitcnt vmcnt(8)
	s_waitcnt lgkmcnt(0)
	s_barrier
	s_setprio 1
	s_waitcnt lgkmcnt(0)
	v_mfma_f32_16x16x32_bf16 v[60:63], v[142:145], v[184:187], v[60:63]
	v_mfma_f32_16x16x32_bf16 v[56:59], v[160:163], v[184:187], v[56:59]
	v_mfma_f32_16x16x32_bf16 v[44:47], v[142:145], v[208:211], v[44:47]
	v_mfma_f32_16x16x32_bf16 v[40:43], v[160:163], v[208:211], v[40:43]
	v_mfma_f32_16x16x32_bf16 v[28:31], v[142:145], v[216:219], v[28:31]
	v_mfma_f32_16x16x32_bf16 v[24:27], v[160:163], v[216:219], v[24:27]
	v_mfma_f32_16x16x32_bf16 v[12:15], v[142:145], v[224:227], v[12:15]
	v_mfma_f32_16x16x32_bf16 v[8:11], v[160:163], v[224:227], v[8:11]
	v_mfma_f32_16x16x32_bf16 v[60:63], v[156:159], v[204:207], v[60:63]
	v_mfma_f32_16x16x32_bf16 v[56:59], v[164:167], v[204:207], v[56:59]
	v_mfma_f32_16x16x32_bf16 v[44:47], v[156:159], v[212:215], v[44:47]
	v_mfma_f32_16x16x32_bf16 v[40:43], v[164:167], v[212:215], v[40:43]
	v_mfma_f32_16x16x32_bf16 v[28:31], v[156:159], v[220:223], v[28:31]
	v_mfma_f32_16x16x32_bf16 v[24:27], v[164:167], v[220:223], v[24:27]
	v_mfma_f32_16x16x32_bf16 v[12:15], v[156:159], v[228:231], v[12:15]
	v_mfma_f32_16x16x32_bf16 v[8:11], v[164:167], v[228:231], v[8:11]
	s_setprio 0
	s_setprio 1
	v_mfma_f32_16x16x32_bf16 v[52:55], v[168:171], v[184:187], v[52:55]
	v_mfma_f32_16x16x32_bf16 v[48:51], v[176:179], v[184:187], v[48:51]
	v_mfma_f32_16x16x32_bf16 v[36:39], v[168:171], v[208:211], v[36:39]
	v_mfma_f32_16x16x32_bf16 v[32:35], v[176:179], v[208:211], v[32:35]
	v_mfma_f32_16x16x32_bf16 v[20:23], v[168:171], v[216:219], v[20:23]
	v_mfma_f32_16x16x32_bf16 v[16:19], v[176:179], v[216:219], v[16:19]
	v_mfma_f32_16x16x32_bf16 v[4:7], v[168:171], v[224:227], v[4:7]
	v_mfma_f32_16x16x32_bf16 v[0:3], v[176:179], v[224:227], v[0:3]
	v_mfma_f32_16x16x32_bf16 v[52:55], v[172:175], v[204:207], v[52:55]
	v_mfma_f32_16x16x32_bf16 v[48:51], v[180:183], v[204:207], v[48:51]
	v_mfma_f32_16x16x32_bf16 v[36:39], v[172:175], v[212:215], v[36:39]
	v_mfma_f32_16x16x32_bf16 v[32:35], v[180:183], v[212:215], v[32:35]
	v_mfma_f32_16x16x32_bf16 v[20:23], v[172:175], v[220:223], v[20:23]
	v_mfma_f32_16x16x32_bf16 v[16:19], v[180:183], v[220:223], v[16:19]
	v_mfma_f32_16x16x32_bf16 v[4:7], v[172:175], v[228:231], v[4:7]
	v_mfma_f32_16x16x32_bf16 v[0:3], v[180:183], v[228:231], v[0:3]
	s_setprio 0
	s_barrier
	s_add_i32 s31, s31, 2
	s_add_u32 s4, s4, 0x100
	s_addc_u32 s5, s5, 0
	s_add_u32 s29, s29, 0x100
	s_addc_u32 s30, s30, 0
	s_cmp_gt_u32 s31, 13
	s_cbranch_scc0 .LBB0_155
	s_nop 0
	v_readlane_b32 s4, v253, 24
	v_readlane_b32 s5, v253, 25
	v_readlane_b32 s28, v254, 47
	s_and_b64 vcc, exec, s[4:5]
	v_readlane_b32 s29, v254, 48
	s_cbranch_vccz .LBB0_158
	s_barrier
